# bf16 GEMM K-loops too: first K-iteration peeled with srcC = 0 on each accumulator's first MFMA, per-unit zeroing deleted (all nine GEMM loops)
# speedup vs baseline: 1.0076x; 1.0046x over previous
.LBB0_250:
	s_add_u32 s8, s8, 0x80080
	s_addc_u32 s9, s9, 0
	s_add_u32 s7, s10, 0x100
	s_addc_u32 s35, s11, 0
	s_mov_b32 s45, -2
	ds_read_b128 v[130:133], v158
	ds_read_b128 v[134:137], v158 offset:1024
	ds_read_b128 v[138:141], v158 offset:2048
	ds_read_b128 v[142:145], v158 offset:3072
	ds_read_b128 v[146:149], v159
	ds_read_b128 v[162:165], v159 offset:1024
	ds_read_b128 v[166:169], v159 offset:2048
	ds_read_b128 v[170:173], v159 offset:3072
	s_add_u32 s10, s8, 0xfff80080
	s_addc_u32 s11, s9, -1
	s_cmp_eq_u32 s45, 28
	s_cselect_b32 s11, s37, s11
	s_cselect_b32 s10, s36, s10
	s_cselect_b32 s43, s39, s35
	s_cselect_b32 s42, s38, s7
	v_mov_b32_e32 v128, v153
	v_mov_b32_e32 v150, v154
	s_add_i32 m0, s52, 0xc000
	ds_read_b128 v[174:177], v160
	ds_read_b128 v[178:181], v160 offset:1024
	ds_read_b128 v[182:185], v160 offset:2048
	ds_read_b128 v[186:189], v160 offset:3072
	ds_read_b128 v[190:193], v160 offset:4096
	ds_read_b128 v[194:197], v160 offset:5120
	ds_read_b128 v[198:201], v160 offset:6144
	ds_read_b128 v[202:205], v160 offset:7168
	s_nop 0
	global_load_lds_dwordx4 v128, s[8:9]
	s_add_i32 m0, s52, 0xe000
	s_nop 0
	global_load_lds_dwordx4 v150, s[8:9]
	s_waitcnt vmcnt(8)
	s_waitcnt lgkmcnt(0)
	s_barrier
	s_setprio 1
	s_waitcnt lgkmcnt(0)
	v_mfma_f32_16x16x32_bf16 v[124:127], v[130:133], v[174:177], 0
	v_mfma_f32_16x16x32_bf16 v[120:123], v[138:141], v[174:177], 0
	v_mfma_f32_16x16x32_bf16 v[108:111], v[130:133], v[182:185], 0
	v_mfma_f32_16x16x32_bf16 v[104:107], v[138:141], v[182:185], 0
	v_mfma_f32_16x16x32_bf16 v[92:95], v[130:133], v[190:193], 0
	v_mfma_f32_16x16x32_bf16 v[88:91], v[138:141], v[190:193], 0
	v_mfma_f32_16x16x32_bf16 v[76:79], v[130:133], v[198:201], 0
	v_mfma_f32_16x16x32_bf16 v[72:75], v[138:141], v[198:201], 0
	v_mfma_f32_16x16x32_bf16 v[124:127], v[134:137], v[178:181], v[124:127]
	v_mfma_f32_16x16x32_bf16 v[120:123], v[142:145], v[178:181], v[120:123]
	v_mfma_f32_16x16x32_bf16 v[108:111], v[134:137], v[186:189], v[108:111]
	v_mfma_f32_16x16x32_bf16 v[104:107], v[142:145], v[186:189], v[104:107]
	v_mfma_f32_16x16x32_bf16 v[92:95], v[134:137], v[194:197], v[92:95]
	v_mfma_f32_16x16x32_bf16 v[88:91], v[142:145], v[194:197], v[88:91]
	v_mfma_f32_16x16x32_bf16 v[76:79], v[134:137], v[202:205], v[76:79]
	v_mfma_f32_16x16x32_bf16 v[72:75], v[142:145], v[202:205], v[72:75]
	s_setprio 0
	s_setprio 1
	v_mfma_f32_16x16x32_bf16 v[116:119], v[146:149], v[174:177], 0
	v_mfma_f32_16x16x32_bf16 v[112:115], v[166:169], v[174:177], 0
	v_mfma_f32_16x16x32_bf16 v[100:103], v[146:149], v[182:185], 0
	v_mfma_f32_16x16x32_bf16 v[96:99], v[166:169], v[182:185], 0
	v_mfma_f32_16x16x32_bf16 v[84:87], v[146:149], v[190:193], 0
	v_mfma_f32_16x16x32_bf16 v[80:83], v[166:169], v[190:193], 0
	v_mfma_f32_16x16x32_bf16 v[68:71], v[146:149], v[198:201], 0
	v_mfma_f32_16x16x32_bf16 v[64:67], v[166:169], v[198:201], 0
	v_mfma_f32_16x16x32_bf16 v[116:119], v[162:165], v[178:181], v[116:119]
	v_mfma_f32_16x16x32_bf16 v[112:115], v[170:173], v[178:181], v[112:115]
	v_mfma_f32_16x16x32_bf16 v[100:103], v[162:165], v[186:189], v[100:103]
	v_mfma_f32_16x16x32_bf16 v[96:99], v[170:173], v[186:189], v[96:99]
	v_mfma_f32_16x16x32_bf16 v[84:87], v[162:165], v[194:197], v[84:87]
	v_mfma_f32_16x16x32_bf16 v[80:83], v[170:173], v[194:197], v[80:83]
	v_mfma_f32_16x16x32_bf16 v[68:71], v[162:165], v[202:205], v[68:71]
	v_mfma_f32_16x16x32_bf16 v[64:67], v[170:173], v[202:205], v[64:67]
	s_setprio 0
	s_barrier
	s_add_i32 s46, s74, s3
	v_mov_b32_e32 v128, v155
	v_mov_b32_e32 v150, v156
	s_mov_b32 m0, s46
	ds_read_b128 v[174:177], v160 offset:16384
	ds_read_b128 v[178:181], v160 offset:17408
	ds_read_b128 v[182:185], v160 offset:18432
	ds_read_b128 v[186:189], v160 offset:19456
	ds_read_b128 v[190:193], v160 offset:20480
	ds_read_b128 v[194:197], v160 offset:21504
	ds_read_b128 v[198:201], v160 offset:22528
	ds_read_b128 v[202:205], v160 offset:23552
	s_nop 0
	global_load_lds_dwordx4 v128, s[42:43]
	s_add_i32 m0, s46, 0x2000
	s_add_u32 s46, s42, 0x80000
	s_addc_u32 s47, s43, 0
	s_add_i32 s48, s75, s3
	global_load_lds_dwordx4 v150, s[42:43]
	v_mov_b32_e32 v128, v155
	v_mov_b32_e32 v150, v156
	s_mov_b32 m0, s48
	s_nop 0
	global_load_lds_dwordx4 v128, s[46:47]
	s_add_i32 m0, s48, 0x2000
	v_mov_b32_e32 v128, v153
	global_load_lds_dwordx4 v150, s[46:47]
	v_mov_b32_e32 v150, v154
	s_mov_b32 m0, s52
	s_nop 0
	global_load_lds_dwordx4 v128, s[10:11]
	s_mov_b32 m0, s53
	s_nop 0
	global_load_lds_dwordx4 v150, s[10:11]
	s_waitcnt vmcnt(8)
	s_waitcnt lgkmcnt(0)
	s_barrier
	s_setprio 1
	s_waitcnt lgkmcnt(0)
	v_mfma_f32_16x16x32_bf16 v[60:63], v[130:133], v[174:177], 0
	v_mfma_f32_16x16x32_bf16 v[56:59], v[138:141], v[174:177], 0
	v_mfma_f32_16x16x32_bf16 v[44:47], v[130:133], v[182:185], 0
	v_mfma_f32_16x16x32_bf16 v[40:43], v[138:141], v[182:185], 0
	v_mfma_f32_16x16x32_bf16 v[28:31], v[130:133], v[190:193], 0
	v_mfma_f32_16x16x32_bf16 v[24:27], v[138:141], v[190:193], 0
	v_mfma_f32_16x16x32_bf16 v[12:15], v[130:133], v[198:201], 0
	v_mfma_f32_16x16x32_bf16 v[8:11], v[138:141], v[198:201], 0
	v_mfma_f32_16x16x32_bf16 v[60:63], v[134:137], v[178:181], v[60:63]
	v_mfma_f32_16x16x32_bf16 v[56:59], v[142:145], v[178:181], v[56:59]
	v_mfma_f32_16x16x32_bf16 v[44:47], v[134:137], v[186:189], v[44:47]
	v_mfma_f32_16x16x32_bf16 v[40:43], v[142:145], v[186:189], v[40:43]
	v_mfma_f32_16x16x32_bf16 v[28:31], v[134:137], v[194:197], v[28:31]
	v_mfma_f32_16x16x32_bf16 v[24:27], v[142:145], v[194:197], v[24:27]
	v_mfma_f32_16x16x32_bf16 v[12:15], v[134:137], v[202:205], v[12:15]
	v_mfma_f32_16x16x32_bf16 v[8:11], v[142:145], v[202:205], v[8:11]
	s_setprio 0
	s_setprio 1
	v_mfma_f32_16x16x32_bf16 v[52:55], v[146:149], v[174:177], 0
	v_mfma_f32_16x16x32_bf16 v[48:51], v[166:169], v[174:177], 0
	v_mfma_f32_16x16x32_bf16 v[36:39], v[146:149], v[182:185], 0
	v_mfma_f32_16x16x32_bf16 v[32:35], v[166:169], v[182:185], 0
	v_mfma_f32_16x16x32_bf16 v[20:23], v[146:149], v[190:193], 0
	v_mfma_f32_16x16x32_bf16 v[16:19], v[166:169], v[190:193], 0
	v_mfma_f32_16x16x32_bf16 v[4:7], v[146:149], v[198:201], 0
	v_mfma_f32_16x16x32_bf16 v[0:3], v[166:169], v[198:201], 0
	v_mfma_f32_16x16x32_bf16 v[52:55], v[162:165], v[178:181], v[52:55]
	v_mfma_f32_16x16x32_bf16 v[48:51], v[170:173], v[178:181], v[48:51]
	v_mfma_f32_16x16x32_bf16 v[36:39], v[162:165], v[186:189], v[36:39]
	v_mfma_f32_16x16x32_bf16 v[32:35], v[170:173], v[186:189], v[32:35]
	v_mfma_f32_16x16x32_bf16 v[20:23], v[162:165], v[194:197], v[20:23]
	v_mfma_f32_16x16x32_bf16 v[16:19], v[170:173], v[194:197], v[16:19]
	v_mfma_f32_16x16x32_bf16 v[4:7], v[162:165], v[202:205], v[4:7]
	v_mfma_f32_16x16x32_bf16 v[0:3], v[170:173], v[202:205], v[0:3]
	s_setprio 0
	s_barrier
	s_add_i32 s48, 0, 0x18000
	v_add_u32_e32 v128, s48, v157
	s_add_i32 s49, 0, 0x1c000
	ds_read_b128 v[130:133], v128
	ds_read_b128 v[134:137], v128 offset:1024
	ds_read_b128 v[138:141], v128 offset:2048
	ds_read_b128 v[142:145], v128 offset:3072
	v_add_u32_e32 v128, s49, v157
	ds_read_b128 v[146:149], v128
	ds_read_b128 v[162:165], v128 offset:1024
	ds_read_b128 v[166:169], v128 offset:2048
	ds_read_b128 v[170:173], v128 offset:3072
	s_add_u32 s46, s10, 0x80000
	v_mov_b32_e32 v128, v153
	v_mov_b32_e32 v150, v154
	s_addc_u32 s47, s11, 0
	s_mov_b32 m0, s54
	ds_read_b128 v[174:177], v160 offset:32768
	ds_read_b128 v[178:181], v160 offset:33792
	ds_read_b128 v[182:185], v160 offset:34816
	ds_read_b128 v[186:189], v160 offset:35840
	ds_read_b128 v[190:193], v160 offset:36864
	ds_read_b128 v[194:197], v160 offset:37888
	ds_read_b128 v[198:201], v160 offset:38912
	ds_read_b128 v[202:205], v160 offset:39936
	s_nop 0
	global_load_lds_dwordx4 v128, s[46:47]
	s_mov_b32 m0, s55
	s_nop 0
	global_load_lds_dwordx4 v150, s[46:47]
	s_waitcnt vmcnt(8)
	s_waitcnt lgkmcnt(0)
	s_barrier
	s_setprio 1
	s_waitcnt lgkmcnt(0)
	v_mfma_f32_16x16x32_bf16 v[124:127], v[130:133], v[174:177], v[124:127]
	v_mfma_f32_16x16x32_bf16 v[120:123], v[138:141], v[174:177], v[120:123]
	v_mfma_f32_16x16x32_bf16 v[108:111], v[130:133], v[182:185], v[108:111]
	v_mfma_f32_16x16x32_bf16 v[104:107], v[138:141], v[182:185], v[104:107]
	v_mfma_f32_16x16x32_bf16 v[92:95], v[130:133], v[190:193], v[92:95]
	v_mfma_f32_16x16x32_bf16 v[88:91], v[138:141], v[190:193], v[88:91]
	v_mfma_f32_16x16x32_bf16 v[76:79], v[130:133], v[198:201], v[76:79]
	v_mfma_f32_16x16x32_bf16 v[72:75], v[138:141], v[198:201], v[72:75]
	v_mfma_f32_16x16x32_bf16 v[124:127], v[134:137], v[178:181], v[124:127]
	v_mfma_f32_16x16x32_bf16 v[120:123], v[142:145], v[178:181], v[120:123]
	v_mfma_f32_16x16x32_bf16 v[108:111], v[134:137], v[186:189], v[108:111]
	v_mfma_f32_16x16x32_bf16 v[104:107], v[142:145], v[186:189], v[104:107]
	v_mfma_f32_16x16x32_bf16 v[92:95], v[134:137], v[194:197], v[92:95]
	v_mfma_f32_16x16x32_bf16 v[88:91], v[142:145], v[194:197], v[88:91]
	v_mfma_f32_16x16x32_bf16 v[76:79], v[134:137], v[202:205], v[76:79]
	v_mfma_f32_16x16x32_bf16 v[72:75], v[142:145], v[202:205], v[72:75]
	s_setprio 0
	s_setprio 1
	v_mfma_f32_16x16x32_bf16 v[116:119], v[146:149], v[174:177], v[116:119]
	v_mfma_f32_16x16x32_bf16 v[112:115], v[166:169], v[174:177], v[112:115]
	v_mfma_f32_16x16x32_bf16 v[100:103], v[146:149], v[182:185], v[100:103]
	v_mfma_f32_16x16x32_bf16 v[96:99], v[166:169], v[182:185], v[96:99]
	v_mfma_f32_16x16x32_bf16 v[84:87], v[146:149], v[190:193], v[84:87]
	v_mfma_f32_16x16x32_bf16 v[80:83], v[166:169], v[190:193], v[80:83]
	v_mfma_f32_16x16x32_bf16 v[68:71], v[146:149], v[198:201], v[68:71]
	v_mfma_f32_16x16x32_bf16 v[64:67], v[166:169], v[198:201], v[64:67]
	v_mfma_f32_16x16x32_bf16 v[116:119], v[162:165], v[178:181], v[116:119]
	v_mfma_f32_16x16x32_bf16 v[112:115], v[170:173], v[178:181], v[112:115]
	v_mfma_f32_16x16x32_bf16 v[100:103], v[162:165], v[186:189], v[100:103]
	v_mfma_f32_16x16x32_bf16 v[96:99], v[170:173], v[186:189], v[96:99]
	v_mfma_f32_16x16x32_bf16 v[84:87], v[162:165], v[194:197], v[84:87]
	v_mfma_f32_16x16x32_bf16 v[80:83], v[170:173], v[194:197], v[80:83]
	v_mfma_f32_16x16x32_bf16 v[68:71], v[162:165], v[202:205], v[68:71]
	v_mfma_f32_16x16x32_bf16 v[64:67], v[170:173], v[202:205], v[64:67]
	s_setprio 0
	s_barrier
	v_mov_b32_e32 v128, v155
	v_mov_b32_e32 v150, v156
	ds_read_b128 v[174:177], v160 offset:49152
	ds_read_b128 v[178:181], v160 offset:50176
	ds_read_b128 v[182:185], v160 offset:51200
	ds_read_b128 v[186:189], v160 offset:52224
	ds_read_b128 v[190:193], v160 offset:53248
	ds_read_b128 v[194:197], v160 offset:54272
	ds_read_b128 v[198:201], v160 offset:55296
	ds_read_b128 v[202:205], v160 offset:56320
	s_add_i32 s46, s48, s3
	v_lshl_add_u64 v[206:207], s[42:43], 0, v[128:129]
	v_lshl_add_u64 v[206:207], v[206:207], 0, s[20:21]
	s_mov_b32 m0, s46
	v_mov_b32_e32 v151, v129
	global_load_lds_dwordx4 v[206:207], off
	s_add_i32 m0, s46, 0x2000
	v_lshl_add_u64 v[150:151], s[42:43], 0, v[150:151]
	s_add_u32 s42, s42, 0x80080
	v_lshl_add_u64 v[150:151], v[150:151], 0, s[20:21]
	s_addc_u32 s43, s43, 0
	s_add_i32 s46, s49, s3
	global_load_lds_dwordx4 v[150:151], off
	v_mov_b32_e32 v128, v155
	v_mov_b32_e32 v150, v156
	s_mov_b32 m0, s46
	v_mov_b32_e32 v151, v129
	global_load_lds_dwordx4 v128, s[42:43]
	s_add_i32 m0, s46, 0x2000
	v_mov_b32_e32 v128, v153
	global_load_lds_dwordx4 v150, s[42:43]
	v_mov_b32_e32 v150, v154
	s_mov_b32 m0, s68
	v_lshl_add_u64 v[206:207], s[10:11], 0, v[128:129]
	v_lshl_add_u64 v[206:207], v[206:207], 0, s[20:21]
	v_lshl_add_u64 v[150:151], s[10:11], 0, v[150:151]
	global_load_lds_dwordx4 v[206:207], off
	v_lshl_add_u64 v[150:151], v[150:151], 0, s[20:21]
	s_mov_b32 m0, s69
	s_nop 0
	global_load_lds_dwordx4 v[150:151], off
	s_waitcnt vmcnt(8)
	s_waitcnt lgkmcnt(0)
	s_barrier
	s_setprio 1
	s_waitcnt lgkmcnt(0)
	v_mfma_f32_16x16x32_bf16 v[60:63], v[130:133], v[174:177], v[60:63]
	v_mfma_f32_16x16x32_bf16 v[56:59], v[138:141], v[174:177], v[56:59]
	v_mfma_f32_16x16x32_bf16 v[44:47], v[130:133], v[182:185], v[44:47]
	v_mfma_f32_16x16x32_bf16 v[40:43], v[138:141], v[182:185], v[40:43]
	v_mfma_f32_16x16x32_bf16 v[28:31], v[130:133], v[190:193], v[28:31]
	v_mfma_f32_16x16x32_bf16 v[24:27], v[138:141], v[190:193], v[24:27]
	v_mfma_f32_16x16x32_bf16 v[12:15], v[130:133], v[198:201], v[12:15]
	v_mfma_f32_16x16x32_bf16 v[8:11], v[138:141], v[198:201], v[8:11]
	v_mfma_f32_16x16x32_bf16 v[60:63], v[134:137], v[178:181], v[60:63]
	v_mfma_f32_16x16x32_bf16 v[56:59], v[142:145], v[178:181], v[56:59]
	v_mfma_f32_16x16x32_bf16 v[44:47], v[134:137], v[186:189], v[44:47]
	v_mfma_f32_16x16x32_bf16 v[40:43], v[142:145], v[186:189], v[40:43]
	v_mfma_f32_16x16x32_bf16 v[28:31], v[134:137], v[194:197], v[28:31]
	v_mfma_f32_16x16x32_bf16 v[24:27], v[142:145], v[194:197], v[24:27]
	v_mfma_f32_16x16x32_bf16 v[12:15], v[134:137], v[202:205], v[12:15]
	v_mfma_f32_16x16x32_bf16 v[8:11], v[142:145], v[202:205], v[8:11]
	s_setprio 0
	s_setprio 1
	v_mfma_f32_16x16x32_bf16 v[52:55], v[146:149], v[174:177], v[52:55]
	v_mfma_f32_16x16x32_bf16 v[48:51], v[166:169], v[174:177], v[48:51]
	v_mfma_f32_16x16x32_bf16 v[36:39], v[146:149], v[182:185], v[36:39]
	v_mfma_f32_16x16x32_bf16 v[32:35], v[166:169], v[182:185], v[32:35]
	v_mfma_f32_16x16x32_bf16 v[20:23], v[146:149], v[190:193], v[20:23]
	v_mfma_f32_16x16x32_bf16 v[16:19], v[166:169], v[190:193], v[16:19]
	v_mfma_f32_16x16x32_bf16 v[4:7], v[146:149], v[198:201], v[4:7]
	v_mfma_f32_16x16x32_bf16 v[0:3], v[166:169], v[198:201], v[0:3]
	v_mfma_f32_16x16x32_bf16 v[52:55], v[162:165], v[178:181], v[52:55]
	v_mfma_f32_16x16x32_bf16 v[48:51], v[170:173], v[178:181], v[48:51]
	v_mfma_f32_16x16x32_bf16 v[36:39], v[162:165], v[186:189], v[36:39]
	v_mfma_f32_16x16x32_bf16 v[32:35], v[170:173], v[186:189], v[32:35]
	v_mfma_f32_16x16x32_bf16 v[20:23], v[162:165], v[194:197], v[20:23]
	v_mfma_f32_16x16x32_bf16 v[16:19], v[170:173], v[194:197], v[16:19]
	v_mfma_f32_16x16x32_bf16 v[4:7], v[162:165], v[202:205], v[4:7]
	v_mfma_f32_16x16x32_bf16 v[0:3], v[170:173], v[202:205], v[0:3]
	s_setprio 0
	s_barrier
	s_add_i32 s45, s45, 2
	s_add_u32 s8, s8, 0x100
	s_addc_u32 s9, s9, 0
	s_add_u32 s7, s7, 0x100
	s_addc_u32 s35, s35, 0
	s_cmp_gt_u32 s45, 29

.LBB0_779:
	s_and_b64 s[6:7], s[42:43], exec
	s_cselect_b32 s88, s39, s45
	s_cselect_b32 s89, s38, s44
	s_cselect_b32 s93, s41, s47
	s_cselect_b32 s94, s40, s46
	s_add_i32 s95, s51, -2
	s_add_u32 s6, s44, 0x70080
	s_addc_u32 s7, s45, 0
	s_add_u32 s96, s46, 0x100
	s_addc_u32 s97, s47, 0
	s_mov_b32 s44, 0
	ds_read_b128 v[134:137], v150
	ds_read_b128 v[138:141], v150 offset:1024
	ds_read_b128 v[142:145], v150 offset:2048
	ds_read_b128 v[154:157], v150 offset:3072
	ds_read_b128 v[158:161], v151
	ds_read_b128 v[162:165], v151 offset:1024
	ds_read_b128 v[166:169], v151 offset:2048
	ds_read_b128 v[170:173], v151 offset:3072
	s_add_i32 s64, s44, 2
	s_add_u32 s46, s6, 0xfff90080
	s_addc_u32 s45, s7, -1
	s_cmp_eq_u32 s95, s44
	s_cselect_b32 s44, s89, s46
	s_cselect_b32 s45, s88, s45
	s_cselect_b32 s47, s93, s97
	s_cselect_b32 s46, s94, s96
	v_mov_b32_e32 v132, v128
	v_mov_b32_e32 v146, v130
	s_add_i32 m0, s37, 0xc000
	ds_read_b128 v[174:177], v152
	ds_read_b128 v[178:181], v152 offset:1024
	ds_read_b128 v[182:185], v152 offset:2048
	ds_read_b128 v[186:189], v152 offset:3072
	ds_read_b128 v[190:193], v152 offset:4096
	ds_read_b128 v[194:197], v152 offset:5120
	ds_read_b128 v[198:201], v152 offset:6144
	ds_read_b128 v[202:205], v152 offset:7168
	s_nop 0
	global_load_lds_dwordx4 v132, s[6:7]
	s_add_i32 m0, s37, 0xe000
	s_nop 0
	global_load_lds_dwordx4 v146, s[6:7]
	s_waitcnt vmcnt(8)
	s_waitcnt lgkmcnt(0)
	s_barrier
	s_setprio 1
	s_waitcnt lgkmcnt(0)
	v_mfma_f32_16x16x32_bf16 v[124:127], v[134:137], v[174:177], 0
	v_mfma_f32_16x16x32_bf16 v[120:123], v[142:145], v[174:177], 0
	v_mfma_f32_16x16x32_bf16 v[108:111], v[134:137], v[182:185], 0
	v_mfma_f32_16x16x32_bf16 v[104:107], v[142:145], v[182:185], 0
	v_mfma_f32_16x16x32_bf16 v[92:95], v[134:137], v[190:193], 0
	v_mfma_f32_16x16x32_bf16 v[88:91], v[142:145], v[190:193], 0
	v_mfma_f32_16x16x32_bf16 v[76:79], v[134:137], v[198:201], 0
	v_mfma_f32_16x16x32_bf16 v[72:75], v[142:145], v[198:201], 0
	v_mfma_f32_16x16x32_bf16 v[124:127], v[138:141], v[178:181], v[124:127]
	v_mfma_f32_16x16x32_bf16 v[120:123], v[154:157], v[178:181], v[120:123]
	v_mfma_f32_16x16x32_bf16 v[108:111], v[138:141], v[186:189], v[108:111]
	v_mfma_f32_16x16x32_bf16 v[104:107], v[154:157], v[186:189], v[104:107]
	v_mfma_f32_16x16x32_bf16 v[92:95], v[138:141], v[194:197], v[92:95]
	v_mfma_f32_16x16x32_bf16 v[88:91], v[154:157], v[194:197], v[88:91]
	v_mfma_f32_16x16x32_bf16 v[76:79], v[138:141], v[202:205], v[76:79]
	v_mfma_f32_16x16x32_bf16 v[72:75], v[154:157], v[202:205], v[72:75]
	s_setprio 0
	s_setprio 1
	v_mfma_f32_16x16x32_bf16 v[116:119], v[158:161], v[174:177], 0
	v_mfma_f32_16x16x32_bf16 v[112:115], v[166:169], v[174:177], 0
	v_mfma_f32_16x16x32_bf16 v[100:103], v[158:161], v[182:185], 0
	v_mfma_f32_16x16x32_bf16 v[96:99], v[166:169], v[182:185], 0
	v_mfma_f32_16x16x32_bf16 v[84:87], v[158:161], v[190:193], 0
	v_mfma_f32_16x16x32_bf16 v[80:83], v[166:169], v[190:193], 0
	v_mfma_f32_16x16x32_bf16 v[68:71], v[158:161], v[198:201], 0
	v_mfma_f32_16x16x32_bf16 v[64:67], v[166:169], v[198:201], 0
	v_mfma_f32_16x16x32_bf16 v[116:119], v[162:165], v[178:181], v[116:119]
	v_mfma_f32_16x16x32_bf16 v[112:115], v[170:173], v[178:181], v[112:115]
	v_mfma_f32_16x16x32_bf16 v[100:103], v[162:165], v[186:189], v[100:103]
	v_mfma_f32_16x16x32_bf16 v[96:99], v[170:173], v[186:189], v[96:99]
	v_mfma_f32_16x16x32_bf16 v[84:87], v[162:165], v[194:197], v[84:87]
	v_mfma_f32_16x16x32_bf16 v[80:83], v[170:173], v[194:197], v[80:83]
	v_mfma_f32_16x16x32_bf16 v[68:71], v[162:165], v[202:205], v[68:71]
	v_mfma_f32_16x16x32_bf16 v[64:67], v[170:173], v[202:205], v[64:67]
	s_setprio 0
	s_barrier
	s_add_i32 s65, s77, s3
	v_mov_b32_e32 v132, v129
	v_mov_b32_e32 v146, v131
	s_mov_b32 m0, s65
	ds_read_b128 v[174:177], v152 offset:16384
	ds_read_b128 v[178:181], v152 offset:17408
	ds_read_b128 v[182:185], v152 offset:18432
	ds_read_b128 v[186:189], v152 offset:19456
	ds_read_b128 v[190:193], v152 offset:20480
	ds_read_b128 v[194:197], v152 offset:21504
	ds_read_b128 v[198:201], v152 offset:22528
	ds_read_b128 v[202:205], v152 offset:23552
	s_nop 0
	global_load_lds_dwordx4 v132, s[46:47]
	s_add_i32 m0, s65, 0x2000
	s_add_u32 vcc_lo, s46, 0x70000
	s_addc_u32 vcc_hi, s47, 0
	s_add_i32 s65, s78, s3
	global_load_lds_dwordx4 v146, s[46:47]
	v_mov_b32_e32 v132, v129
	v_mov_b32_e32 v146, v131
	s_mov_b32 m0, s65
	s_nop 0
	global_load_lds_dwordx4 v132, vcc
	s_add_i32 m0, s65, 0x2000
	v_mov_b32_e32 v132, v128
	global_load_lds_dwordx4 v146, vcc
	v_mov_b32_e32 v146, v130
	s_mov_b32 m0, s37
	s_nop 0
	global_load_lds_dwordx4 v132, s[44:45]
	s_mov_b32 m0, s53
	s_nop 0
	global_load_lds_dwordx4 v146, s[44:45]
	s_waitcnt vmcnt(8)
	s_waitcnt lgkmcnt(0)
	s_barrier
	s_setprio 1
	s_waitcnt lgkmcnt(0)
	v_mfma_f32_16x16x32_bf16 v[60:63], v[134:137], v[174:177], 0
	v_mfma_f32_16x16x32_bf16 v[56:59], v[142:145], v[174:177], 0
	v_mfma_f32_16x16x32_bf16 v[44:47], v[134:137], v[182:185], 0
	v_mfma_f32_16x16x32_bf16 v[40:43], v[142:145], v[182:185], 0
	v_mfma_f32_16x16x32_bf16 v[28:31], v[134:137], v[190:193], 0
	v_mfma_f32_16x16x32_bf16 v[24:27], v[142:145], v[190:193], 0
	v_mfma_f32_16x16x32_bf16 v[12:15], v[134:137], v[198:201], 0
	v_mfma_f32_16x16x32_bf16 v[8:11], v[142:145], v[198:201], 0
	v_mfma_f32_16x16x32_bf16 v[60:63], v[138:141], v[178:181], v[60:63]
	v_mfma_f32_16x16x32_bf16 v[56:59], v[154:157], v[178:181], v[56:59]
	v_mfma_f32_16x16x32_bf16 v[44:47], v[138:141], v[186:189], v[44:47]
	v_mfma_f32_16x16x32_bf16 v[40:43], v[154:157], v[186:189], v[40:43]
	v_mfma_f32_16x16x32_bf16 v[28:31], v[138:141], v[194:197], v[28:31]
	v_mfma_f32_16x16x32_bf16 v[24:27], v[154:157], v[194:197], v[24:27]
	v_mfma_f32_16x16x32_bf16 v[12:15], v[138:141], v[202:205], v[12:15]
	v_mfma_f32_16x16x32_bf16 v[8:11], v[154:157], v[202:205], v[8:11]
	s_setprio 0
	s_setprio 1
	v_mfma_f32_16x16x32_bf16 v[52:55], v[158:161], v[174:177], 0
	v_mfma_f32_16x16x32_bf16 v[48:51], v[166:169], v[174:177], 0
	v_mfma_f32_16x16x32_bf16 v[36:39], v[158:161], v[182:185], 0
	v_mfma_f32_16x16x32_bf16 v[32:35], v[166:169], v[182:185], 0
	v_mfma_f32_16x16x32_bf16 v[20:23], v[158:161], v[190:193], 0
	v_mfma_f32_16x16x32_bf16 v[16:19], v[166:169], v[190:193], 0
	v_mfma_f32_16x16x32_bf16 v[4:7], v[158:161], v[198:201], 0
	v_mfma_f32_16x16x32_bf16 v[0:3], v[166:169], v[198:201], 0
	v_mfma_f32_16x16x32_bf16 v[52:55], v[162:165], v[178:181], v[52:55]
	v_mfma_f32_16x16x32_bf16 v[48:51], v[170:173], v[178:181], v[48:51]
	v_mfma_f32_16x16x32_bf16 v[36:39], v[162:165], v[186:189], v[36:39]
	v_mfma_f32_16x16x32_bf16 v[32:35], v[170:173], v[186:189], v[32:35]
	v_mfma_f32_16x16x32_bf16 v[20:23], v[162:165], v[194:197], v[20:23]
	v_mfma_f32_16x16x32_bf16 v[16:19], v[170:173], v[194:197], v[16:19]
	v_mfma_f32_16x16x32_bf16 v[4:7], v[162:165], v[202:205], v[4:7]
	v_mfma_f32_16x16x32_bf16 v[0:3], v[170:173], v[202:205], v[0:3]
	s_setprio 0
	s_barrier
	s_add_i32 s65, 0, 0x18000
	v_add_u32_e32 v132, s65, v149
	s_add_i32 s75, 0, 0x1c000
	ds_read_b128 v[134:137], v132
	ds_read_b128 v[138:141], v132 offset:1024
	ds_read_b128 v[142:145], v132 offset:2048
	ds_read_b128 v[154:157], v132 offset:3072
	v_add_u32_e32 v132, s75, v149
	ds_read_b128 v[158:161], v132
	ds_read_b128 v[162:165], v132 offset:1024
	ds_read_b128 v[166:169], v132 offset:2048
	ds_read_b128 v[170:173], v132 offset:3072
	s_add_u32 vcc_lo, s44, 0x70000
	v_mov_b32_e32 v132, v128
	v_mov_b32_e32 v146, v130
	s_addc_u32 vcc_hi, s45, 0
	s_mov_b32 m0, s54
	ds_read_b128 v[174:177], v152 offset:32768
	ds_read_b128 v[178:181], v152 offset:33792
	ds_read_b128 v[182:185], v152 offset:34816
	ds_read_b128 v[186:189], v152 offset:35840
	ds_read_b128 v[190:193], v152 offset:36864
	ds_read_b128 v[194:197], v152 offset:37888
	ds_read_b128 v[198:201], v152 offset:38912
	ds_read_b128 v[202:205], v152 offset:39936
	s_nop 0
	global_load_lds_dwordx4 v132, vcc
	s_mov_b32 m0, s55
	s_nop 0
	global_load_lds_dwordx4 v146, vcc
	s_waitcnt vmcnt(8)
	s_waitcnt lgkmcnt(0)
	s_barrier
	s_setprio 1
	s_waitcnt lgkmcnt(0)
	v_mfma_f32_16x16x32_bf16 v[124:127], v[134:137], v[174:177], v[124:127]
	v_mfma_f32_16x16x32_bf16 v[120:123], v[142:145], v[174:177], v[120:123]
	v_mfma_f32_16x16x32_bf16 v[108:111], v[134:137], v[182:185], v[108:111]
	v_mfma_f32_16x16x32_bf16 v[104:107], v[142:145], v[182:185], v[104:107]
	v_mfma_f32_16x16x32_bf16 v[92:95], v[134:137], v[190:193], v[92:95]
	v_mfma_f32_16x16x32_bf16 v[88:91], v[142:145], v[190:193], v[88:91]
	v_mfma_f32_16x16x32_bf16 v[76:79], v[134:137], v[198:201], v[76:79]
	v_mfma_f32_16x16x32_bf16 v[72:75], v[142:145], v[198:201], v[72:75]
	v_mfma_f32_16x16x32_bf16 v[124:127], v[138:141], v[178:181], v[124:127]
	v_mfma_f32_16x16x32_bf16 v[120:123], v[154:157], v[178:181], v[120:123]
	v_mfma_f32_16x16x32_bf16 v[108:111], v[138:141], v[186:189], v[108:111]
	v_mfma_f32_16x16x32_bf16 v[104:107], v[154:157], v[186:189], v[104:107]
	v_mfma_f32_16x16x32_bf16 v[92:95], v[138:141], v[194:197], v[92:95]
	v_mfma_f32_16x16x32_bf16 v[88:91], v[154:157], v[194:197], v[88:91]
	v_mfma_f32_16x16x32_bf16 v[76:79], v[138:141], v[202:205], v[76:79]
	v_mfma_f32_16x16x32_bf16 v[72:75], v[154:157], v[202:205], v[72:75]
	s_setprio 0
	s_setprio 1
	v_mfma_f32_16x16x32_bf16 v[116:119], v[158:161], v[174:177], v[116:119]
	v_mfma_f32_16x16x32_bf16 v[112:115], v[166:169], v[174:177], v[112:115]
	v_mfma_f32_16x16x32_bf16 v[100:103], v[158:161], v[182:185], v[100:103]
	v_mfma_f32_16x16x32_bf16 v[96:99], v[166:169], v[182:185], v[96:99]
	v_mfma_f32_16x16x32_bf16 v[84:87], v[158:161], v[190:193], v[84:87]
	v_mfma_f32_16x16x32_bf16 v[80:83], v[166:169], v[190:193], v[80:83]
	v_mfma_f32_16x16x32_bf16 v[68:71], v[158:161], v[198:201], v[68:71]
	v_mfma_f32_16x16x32_bf16 v[64:67], v[166:169], v[198:201], v[64:67]
	v_mfma_f32_16x16x32_bf16 v[116:119], v[162:165], v[178:181], v[116:119]
	v_mfma_f32_16x16x32_bf16 v[112:115], v[170:173], v[178:181], v[112:115]
	v_mfma_f32_16x16x32_bf16 v[100:103], v[162:165], v[186:189], v[100:103]
	v_mfma_f32_16x16x32_bf16 v[96:99], v[170:173], v[186:189], v[96:99]
	v_mfma_f32_16x16x32_bf16 v[84:87], v[162:165], v[194:197], v[84:87]
	v_mfma_f32_16x16x32_bf16 v[80:83], v[170:173], v[194:197], v[80:83]
	v_mfma_f32_16x16x32_bf16 v[68:71], v[162:165], v[202:205], v[68:71]
	v_mfma_f32_16x16x32_bf16 v[64:67], v[170:173], v[202:205], v[64:67]
	s_setprio 0
	s_barrier
	v_mov_b32_e32 v132, v129
	v_mov_b32_e32 v146, v131
	ds_read_b128 v[174:177], v152 offset:49152
	ds_read_b128 v[178:181], v152 offset:50176
	ds_read_b128 v[182:185], v152 offset:51200
	ds_read_b128 v[186:189], v152 offset:52224
	ds_read_b128 v[190:193], v152 offset:53248
	ds_read_b128 v[194:197], v152 offset:54272
	ds_read_b128 v[198:201], v152 offset:55296
	ds_read_b128 v[202:205], v152 offset:56320
	s_add_i32 s65, s65, s3
	v_lshl_add_u64 v[206:207], s[46:47], 0, v[132:133]
	v_lshl_add_u64 v[206:207], v[206:207], 0, s[14:15]
	s_mov_b32 m0, s65
	v_mov_b32_e32 v147, v133
	global_load_lds_dwordx4 v[206:207], off
	s_add_i32 m0, s65, 0x2000
	v_lshl_add_u64 v[146:147], s[46:47], 0, v[146:147]
	s_add_u32 s46, s46, 0x70080
	v_lshl_add_u64 v[146:147], v[146:147], 0, s[14:15]
	s_addc_u32 s47, s47, 0
	s_add_i32 s65, s75, s3
	global_load_lds_dwordx4 v[146:147], off
	v_mov_b32_e32 v132, v129
	v_mov_b32_e32 v146, v131
	s_mov_b32 m0, s65
	v_mov_b32_e32 v147, v133
	global_load_lds_dwordx4 v132, s[46:47]
	s_add_i32 m0, s65, 0x2000
	v_mov_b32_e32 v132, v128
	global_load_lds_dwordx4 v146, s[46:47]
	v_mov_b32_e32 v146, v130
	s_mov_b32 m0, s68
	v_lshl_add_u64 v[206:207], s[44:45], 0, v[132:133]
	v_lshl_add_u64 v[206:207], v[206:207], 0, s[14:15]
	v_lshl_add_u64 v[146:147], s[44:45], 0, v[146:147]
	global_load_lds_dwordx4 v[206:207], off
	v_lshl_add_u64 v[146:147], v[146:147], 0, s[14:15]
	s_mov_b32 m0, s69
	s_nop 0
	global_load_lds_dwordx4 v[146:147], off
	s_waitcnt vmcnt(8)
	s_waitcnt lgkmcnt(0)
	s_barrier
	s_setprio 1
	s_waitcnt lgkmcnt(0)
	v_mfma_f32_16x16x32_bf16 v[60:63], v[134:137], v[174:177], v[60:63]
	v_mfma_f32_16x16x32_bf16 v[56:59], v[142:145], v[174:177], v[56:59]
	v_mfma_f32_16x16x32_bf16 v[44:47], v[134:137], v[182:185], v[44:47]
	v_mfma_f32_16x16x32_bf16 v[40:43], v[142:145], v[182:185], v[40:43]
	v_mfma_f32_16x16x32_bf16 v[28:31], v[134:137], v[190:193], v[28:31]
	v_mfma_f32_16x16x32_bf16 v[24:27], v[142:145], v[190:193], v[24:27]
	v_mfma_f32_16x16x32_bf16 v[12:15], v[134:137], v[198:201], v[12:15]
	v_mfma_f32_16x16x32_bf16 v[8:11], v[142:145], v[198:201], v[8:11]
	v_mfma_f32_16x16x32_bf16 v[60:63], v[138:141], v[178:181], v[60:63]
	v_mfma_f32_16x16x32_bf16 v[56:59], v[154:157], v[178:181], v[56:59]
	v_mfma_f32_16x16x32_bf16 v[44:47], v[138:141], v[186:189], v[44:47]
	v_mfma_f32_16x16x32_bf16 v[40:43], v[154:157], v[186:189], v[40:43]
	v_mfma_f32_16x16x32_bf16 v[28:31], v[138:141], v[194:197], v[28:31]
	v_mfma_f32_16x16x32_bf16 v[24:27], v[154:157], v[194:197], v[24:27]
	v_mfma_f32_16x16x32_bf16 v[12:15], v[138:141], v[202:205], v[12:15]
	v_mfma_f32_16x16x32_bf16 v[8:11], v[154:157], v[202:205], v[8:11]
	s_setprio 0
	s_setprio 1
	v_mfma_f32_16x16x32_bf16 v[52:55], v[158:161], v[174:177], v[52:55]
	v_mfma_f32_16x16x32_bf16 v[48:51], v[166:169], v[174:177], v[48:51]
	v_mfma_f32_16x16x32_bf16 v[36:39], v[158:161], v[182:185], v[36:39]
	v_mfma_f32_16x16x32_bf16 v[32:35], v[166:169], v[182:185], v[32:35]
	v_mfma_f32_16x16x32_bf16 v[20:23], v[158:161], v[190:193], v[20:23]
	v_mfma_f32_16x16x32_bf16 v[16:19], v[166:169], v[190:193], v[16:19]
	v_mfma_f32_16x16x32_bf16 v[4:7], v[158:161], v[198:201], v[4:7]
	v_mfma_f32_16x16x32_bf16 v[0:3], v[166:169], v[198:201], v[0:3]
	v_mfma_f32_16x16x32_bf16 v[52:55], v[162:165], v[178:181], v[52:55]
	v_mfma_f32_16x16x32_bf16 v[48:51], v[170:173], v[178:181], v[48:51]
	v_mfma_f32_16x16x32_bf16 v[36:39], v[162:165], v[186:189], v[36:39]
	v_mfma_f32_16x16x32_bf16 v[32:35], v[170:173], v[186:189], v[32:35]
	v_mfma_f32_16x16x32_bf16 v[20:23], v[162:165], v[194:197], v[20:23]
	v_mfma_f32_16x16x32_bf16 v[16:19], v[170:173], v[194:197], v[16:19]
	v_mfma_f32_16x16x32_bf16 v[4:7], v[162:165], v[202:205], v[4:7]
	v_mfma_f32_16x16x32_bf16 v[0:3], v[170:173], v[202:205], v[0:3]
	s_setprio 0
	s_barrier
	s_add_u32 s6, s6, 0x100
	s_addc_u32 s7, s7, 0
	s_add_u32 s96, s96, 0x100
	s_addc_u32 s97, s97, 0
	s_cmp_ge_i32 s64, s51
	s_mov_b32 s44, s64

.LBB0_1926:
	s_add_u32 s54, s54, 0x80080
	s_addc_u32 s55, s55, 0
	s_add_u32 s7, s66, 0x100
	s_addc_u32 s9, s67, 0
	s_mov_b32 s14, -2
	ds_read_b128 v[162:165], v192
	ds_read_b128 v[166:169], v192 offset:1024
	ds_read_b128 v[170:173], v192 offset:2048
	ds_read_b128 v[174:177], v192 offset:3072
	ds_read_b128 v[178:181], v193
	ds_read_b128 v[182:185], v193 offset:1024
	ds_read_b128 v[196:199], v193 offset:2048
	ds_read_b128 v[200:203], v193 offset:3072
	s_add_u32 s43, s54, 0xfff80080
	s_addc_u32 s48, s55, -1
	s_cmp_eq_u32 s14, 28
	s_cselect_b32 s67, s47, s48
	s_cselect_b32 s66, s46, s43
	s_cselect_b32 s69, s45, s9
	s_cselect_b32 s68, s44, s7
	v_mov_b32_e32 v160, v187
	v_mov_b32_e32 v195, v188
	s_add_i32 m0, s39, 0xc000
	ds_read_b128 v[204:207], v194
	ds_read_b128 v[208:211], v194 offset:1024
	ds_read_b128 v[212:215], v194 offset:2048
	ds_read_b128 v[216:219], v194 offset:3072
	ds_read_b128 v[220:223], v194 offset:4096
	ds_read_b128 v[224:227], v194 offset:5120
	ds_read_b128 v[228:231], v194 offset:6144
	ds_read_b128 v[232:235], v194 offset:7168
	s_nop 0
	global_load_lds_dwordx4 v160, s[54:55]
	s_add_i32 m0, s39, 0xe000
	s_nop 0
	global_load_lds_dwordx4 v195, s[54:55]
	s_waitcnt vmcnt(8)
	s_waitcnt lgkmcnt(0)
	s_barrier
	s_setprio 1
	s_waitcnt lgkmcnt(0)
	v_mfma_f32_16x16x32_bf16 v[156:159], v[162:165], v[204:207], 0
	v_mfma_f32_16x16x32_bf16 v[152:155], v[170:173], v[204:207], 0
	v_mfma_f32_16x16x32_bf16 v[140:143], v[162:165], v[212:215], 0
	v_mfma_f32_16x16x32_bf16 v[136:139], v[170:173], v[212:215], 0
	v_mfma_f32_16x16x32_bf16 v[124:127], v[162:165], v[220:223], 0
	v_mfma_f32_16x16x32_bf16 v[120:123], v[170:173], v[220:223], 0
	v_mfma_f32_16x16x32_bf16 v[108:111], v[162:165], v[228:231], 0
	v_mfma_f32_16x16x32_bf16 v[104:107], v[170:173], v[228:231], 0
	v_mfma_f32_16x16x32_bf16 v[156:159], v[166:169], v[208:211], v[156:159]
	v_mfma_f32_16x16x32_bf16 v[152:155], v[174:177], v[208:211], v[152:155]
	v_mfma_f32_16x16x32_bf16 v[140:143], v[166:169], v[216:219], v[140:143]
	v_mfma_f32_16x16x32_bf16 v[136:139], v[174:177], v[216:219], v[136:139]
	v_mfma_f32_16x16x32_bf16 v[124:127], v[166:169], v[224:227], v[124:127]
	v_mfma_f32_16x16x32_bf16 v[120:123], v[174:177], v[224:227], v[120:123]
	v_mfma_f32_16x16x32_bf16 v[108:111], v[166:169], v[232:235], v[108:111]
	v_mfma_f32_16x16x32_bf16 v[104:107], v[174:177], v[232:235], v[104:107]
	s_setprio 0
	s_setprio 1
	v_mfma_f32_16x16x32_bf16 v[148:151], v[178:181], v[204:207], 0
	v_mfma_f32_16x16x32_bf16 v[144:147], v[196:199], v[204:207], 0
	v_mfma_f32_16x16x32_bf16 v[132:135], v[178:181], v[212:215], 0
	v_mfma_f32_16x16x32_bf16 v[128:131], v[196:199], v[212:215], 0
	v_mfma_f32_16x16x32_bf16 v[116:119], v[178:181], v[220:223], 0
	v_mfma_f32_16x16x32_bf16 v[112:115], v[196:199], v[220:223], 0
	v_mfma_f32_16x16x32_bf16 v[100:103], v[178:181], v[228:231], 0
	v_mfma_f32_16x16x32_bf16 v[96:99], v[196:199], v[228:231], 0
	v_mfma_f32_16x16x32_bf16 v[148:151], v[182:185], v[208:211], v[148:151]
	v_mfma_f32_16x16x32_bf16 v[144:147], v[200:203], v[208:211], v[144:147]
	v_mfma_f32_16x16x32_bf16 v[132:135], v[182:185], v[216:219], v[132:135]
	v_mfma_f32_16x16x32_bf16 v[128:131], v[200:203], v[216:219], v[128:131]
	v_mfma_f32_16x16x32_bf16 v[116:119], v[182:185], v[224:227], v[116:119]
	v_mfma_f32_16x16x32_bf16 v[112:115], v[200:203], v[224:227], v[112:115]
	v_mfma_f32_16x16x32_bf16 v[100:103], v[182:185], v[232:235], v[100:103]
	v_mfma_f32_16x16x32_bf16 v[96:99], v[200:203], v[232:235], v[96:99]
	s_setprio 0
	s_barrier
	s_add_i32 s43, s87, s3
	v_mov_b32_e32 v160, v189
	v_mov_b32_e32 v195, v190
	s_mov_b32 m0, s43
	ds_read_b128 v[204:207], v194 offset:16384
	ds_read_b128 v[208:211], v194 offset:17408
	ds_read_b128 v[212:215], v194 offset:18432
	ds_read_b128 v[216:219], v194 offset:19456
	ds_read_b128 v[220:223], v194 offset:20480
	ds_read_b128 v[224:227], v194 offset:21504
	ds_read_b128 v[228:231], v194 offset:22528
	ds_read_b128 v[232:235], v194 offset:23552
	s_nop 0
	global_load_lds_dwordx4 v160, s[68:69]
	s_add_i32 m0, s43, 0x2000
	s_add_u32 s48, s68, 0x80000
	s_addc_u32 s49, s69, 0
	s_add_i32 s43, s88, s3
	global_load_lds_dwordx4 v195, s[68:69]
	v_mov_b32_e32 v160, v189
	v_mov_b32_e32 v195, v190
	s_mov_b32 m0, s43
	s_nop 0
	global_load_lds_dwordx4 v160, s[48:49]
	s_add_i32 m0, s43, 0x2000
	v_mov_b32_e32 v160, v187
	global_load_lds_dwordx4 v195, s[48:49]
	v_mov_b32_e32 v195, v188
	s_mov_b32 m0, s39
	s_nop 0
	global_load_lds_dwordx4 v160, s[66:67]
	s_mov_b32 m0, s63
	s_nop 0
	global_load_lds_dwordx4 v195, s[66:67]
	s_waitcnt vmcnt(8)
	s_waitcnt lgkmcnt(0)
	s_barrier
	s_setprio 1
	s_waitcnt lgkmcnt(0)
	v_mfma_f32_16x16x32_bf16 v[92:95], v[162:165], v[204:207], 0
	v_mfma_f32_16x16x32_bf16 v[88:91], v[170:173], v[204:207], 0
	v_mfma_f32_16x16x32_bf16 v[76:79], v[162:165], v[212:215], 0
	v_mfma_f32_16x16x32_bf16 v[72:75], v[170:173], v[212:215], 0
	v_mfma_f32_16x16x32_bf16 v[60:63], v[162:165], v[220:223], 0
	v_mfma_f32_16x16x32_bf16 v[56:59], v[170:173], v[220:223], 0
	v_mfma_f32_16x16x32_bf16 v[44:47], v[162:165], v[228:231], 0
	v_mfma_f32_16x16x32_bf16 v[40:43], v[170:173], v[228:231], 0
	v_mfma_f32_16x16x32_bf16 v[92:95], v[166:169], v[208:211], v[92:95]
	v_mfma_f32_16x16x32_bf16 v[88:91], v[174:177], v[208:211], v[88:91]
	v_mfma_f32_16x16x32_bf16 v[76:79], v[166:169], v[216:219], v[76:79]
	v_mfma_f32_16x16x32_bf16 v[72:75], v[174:177], v[216:219], v[72:75]
	v_mfma_f32_16x16x32_bf16 v[60:63], v[166:169], v[224:227], v[60:63]
	v_mfma_f32_16x16x32_bf16 v[56:59], v[174:177], v[224:227], v[56:59]
	v_mfma_f32_16x16x32_bf16 v[44:47], v[166:169], v[232:235], v[44:47]
	v_mfma_f32_16x16x32_bf16 v[40:43], v[174:177], v[232:235], v[40:43]
	s_setprio 0
	s_setprio 1
	v_mfma_f32_16x16x32_bf16 v[84:87], v[178:181], v[204:207], 0
	v_mfma_f32_16x16x32_bf16 v[80:83], v[196:199], v[204:207], 0
	v_mfma_f32_16x16x32_bf16 v[68:71], v[178:181], v[212:215], 0
	v_mfma_f32_16x16x32_bf16 v[64:67], v[196:199], v[212:215], 0
	v_mfma_f32_16x16x32_bf16 v[52:55], v[178:181], v[220:223], 0
	v_mfma_f32_16x16x32_bf16 v[48:51], v[196:199], v[220:223], 0
	v_mfma_f32_16x16x32_bf16 v[32:35], v[178:181], v[228:231], 0
	v_mfma_f32_16x16x32_bf16 v[36:39], v[196:199], v[228:231], 0
	v_mfma_f32_16x16x32_bf16 v[84:87], v[182:185], v[208:211], v[84:87]
	v_mfma_f32_16x16x32_bf16 v[80:83], v[200:203], v[208:211], v[80:83]
	v_mfma_f32_16x16x32_bf16 v[68:71], v[182:185], v[216:219], v[68:71]
	v_mfma_f32_16x16x32_bf16 v[64:67], v[200:203], v[216:219], v[64:67]
	v_mfma_f32_16x16x32_bf16 v[52:55], v[182:185], v[224:227], v[52:55]
	v_mfma_f32_16x16x32_bf16 v[48:51], v[200:203], v[224:227], v[48:51]
	v_mfma_f32_16x16x32_bf16 v[32:35], v[182:185], v[232:235], v[32:35]
	v_mfma_f32_16x16x32_bf16 v[36:39], v[200:203], v[232:235], v[36:39]
	s_setprio 0
	s_barrier
	s_add_i32 s43, 0, 0x18000
	v_add_u32_e32 v160, s43, v191
	s_add_i32 s64, 0, 0x1c000
	ds_read_b128 v[162:165], v160
	ds_read_b128 v[166:169], v160 offset:1024
	ds_read_b128 v[170:173], v160 offset:2048
	ds_read_b128 v[174:177], v160 offset:3072
	v_add_u32_e32 v160, s64, v191
	ds_read_b128 v[178:181], v160
	ds_read_b128 v[182:185], v160 offset:1024
	ds_read_b128 v[196:199], v160 offset:2048
	ds_read_b128 v[200:203], v160 offset:3072
	s_add_u32 s48, s66, 0x80000
	v_mov_b32_e32 v160, v187
	v_mov_b32_e32 v195, v188
	s_addc_u32 s49, s67, 0
	s_mov_b32 m0, s74
	ds_read_b128 v[204:207], v194 offset:32768
	ds_read_b128 v[208:211], v194 offset:33792
	ds_read_b128 v[212:215], v194 offset:34816
	ds_read_b128 v[216:219], v194 offset:35840
	ds_read_b128 v[220:223], v194 offset:36864
	ds_read_b128 v[224:227], v194 offset:37888
	ds_read_b128 v[228:231], v194 offset:38912
	ds_read_b128 v[232:235], v194 offset:39936
	s_nop 0
	global_load_lds_dwordx4 v160, s[48:49]
	s_mov_b32 m0, s75
	s_nop 0
	global_load_lds_dwordx4 v195, s[48:49]
	s_waitcnt vmcnt(8)
	s_waitcnt lgkmcnt(0)
	s_barrier
	s_setprio 1
	s_waitcnt lgkmcnt(0)
	v_mfma_f32_16x16x32_bf16 v[156:159], v[162:165], v[204:207], v[156:159]
	v_mfma_f32_16x16x32_bf16 v[152:155], v[170:173], v[204:207], v[152:155]
	v_mfma_f32_16x16x32_bf16 v[140:143], v[162:165], v[212:215], v[140:143]
	v_mfma_f32_16x16x32_bf16 v[136:139], v[170:173], v[212:215], v[136:139]
	v_mfma_f32_16x16x32_bf16 v[124:127], v[162:165], v[220:223], v[124:127]
	v_mfma_f32_16x16x32_bf16 v[120:123], v[170:173], v[220:223], v[120:123]
	v_mfma_f32_16x16x32_bf16 v[108:111], v[162:165], v[228:231], v[108:111]
	v_mfma_f32_16x16x32_bf16 v[104:107], v[170:173], v[228:231], v[104:107]
	v_mfma_f32_16x16x32_bf16 v[156:159], v[166:169], v[208:211], v[156:159]
	v_mfma_f32_16x16x32_bf16 v[152:155], v[174:177], v[208:211], v[152:155]
	v_mfma_f32_16x16x32_bf16 v[140:143], v[166:169], v[216:219], v[140:143]
	v_mfma_f32_16x16x32_bf16 v[136:139], v[174:177], v[216:219], v[136:139]
	v_mfma_f32_16x16x32_bf16 v[124:127], v[166:169], v[224:227], v[124:127]
	v_mfma_f32_16x16x32_bf16 v[120:123], v[174:177], v[224:227], v[120:123]
	v_mfma_f32_16x16x32_bf16 v[108:111], v[166:169], v[232:235], v[108:111]
	v_mfma_f32_16x16x32_bf16 v[104:107], v[174:177], v[232:235], v[104:107]
	s_setprio 0
	s_setprio 1
	v_mfma_f32_16x16x32_bf16 v[148:151], v[178:181], v[204:207], v[148:151]
	v_mfma_f32_16x16x32_bf16 v[144:147], v[196:199], v[204:207], v[144:147]
	v_mfma_f32_16x16x32_bf16 v[132:135], v[178:181], v[212:215], v[132:135]
	v_mfma_f32_16x16x32_bf16 v[128:131], v[196:199], v[212:215], v[128:131]
	v_mfma_f32_16x16x32_bf16 v[116:119], v[178:181], v[220:223], v[116:119]
	v_mfma_f32_16x16x32_bf16 v[112:115], v[196:199], v[220:223], v[112:115]
	v_mfma_f32_16x16x32_bf16 v[100:103], v[178:181], v[228:231], v[100:103]
	v_mfma_f32_16x16x32_bf16 v[96:99], v[196:199], v[228:231], v[96:99]
	v_mfma_f32_16x16x32_bf16 v[148:151], v[182:185], v[208:211], v[148:151]
	v_mfma_f32_16x16x32_bf16 v[144:147], v[200:203], v[208:211], v[144:147]
	v_mfma_f32_16x16x32_bf16 v[132:135], v[182:185], v[216:219], v[132:135]
	v_mfma_f32_16x16x32_bf16 v[128:131], v[200:203], v[216:219], v[128:131]
	v_mfma_f32_16x16x32_bf16 v[116:119], v[182:185], v[224:227], v[116:119]
	v_mfma_f32_16x16x32_bf16 v[112:115], v[200:203], v[224:227], v[112:115]
	v_mfma_f32_16x16x32_bf16 v[100:103], v[182:185], v[232:235], v[100:103]
	v_mfma_f32_16x16x32_bf16 v[96:99], v[200:203], v[232:235], v[96:99]
	s_setprio 0
	s_barrier
	v_mov_b32_e32 v160, v189
	v_mov_b32_e32 v236, v190
	ds_read_b128 v[204:207], v194 offset:49152
	ds_read_b128 v[208:211], v194 offset:50176
	ds_read_b128 v[212:215], v194 offset:51200
	ds_read_b128 v[216:219], v194 offset:52224
	ds_read_b128 v[220:223], v194 offset:53248
	ds_read_b128 v[224:227], v194 offset:54272
	ds_read_b128 v[228:231], v194 offset:55296
	ds_read_b128 v[232:235], v194 offset:56320
	s_add_i32 s43, s43, s3
	v_lshl_add_u64 v[238:239], s[68:69], 0, v[160:161]
	v_lshl_add_u64 v[238:239], v[238:239], 0, s[16:17]
	s_mov_b32 m0, s43
	v_mov_b32_e32 v237, v161
	global_load_lds_dwordx4 v[238:239], off
	s_add_i32 m0, s43, 0x2000
	v_lshl_add_u64 v[236:237], s[68:69], 0, v[236:237]
	s_add_u32 s48, s68, 0x80080
	v_lshl_add_u64 v[236:237], v[236:237], 0, s[16:17]
	v_mov_b32_e32 v160, v189
	v_mov_b32_e32 v195, v190
	s_addc_u32 s49, s69, 0
	s_add_i32 s43, s64, s3
	global_load_lds_dwordx4 v[236:237], off
	s_mov_b32 m0, s43
	v_mov_b32_e32 v236, v188
	global_load_lds_dwordx4 v160, s[48:49]
	s_add_i32 m0, s43, 0x2000
	v_mov_b32_e32 v160, v187
	global_load_lds_dwordx4 v195, s[48:49]
	v_mov_b32_e32 v237, v161
	v_lshl_add_u64 v[238:239], s[66:67], 0, v[160:161]
	v_lshl_add_u64 v[238:239], v[238:239], 0, s[16:17]
	s_mov_b32 m0, s79
	v_lshl_add_u64 v[236:237], s[66:67], 0, v[236:237]
	global_load_lds_dwordx4 v[238:239], off
	v_lshl_add_u64 v[236:237], v[236:237], 0, s[16:17]
	s_mov_b32 m0, s80
	s_nop 0
	global_load_lds_dwordx4 v[236:237], off
	s_waitcnt vmcnt(8)
	s_waitcnt lgkmcnt(0)
	s_barrier
	s_setprio 1
	s_waitcnt lgkmcnt(0)
	v_mfma_f32_16x16x32_bf16 v[92:95], v[162:165], v[204:207], v[92:95]
	v_mfma_f32_16x16x32_bf16 v[88:91], v[170:173], v[204:207], v[88:91]
	v_mfma_f32_16x16x32_bf16 v[76:79], v[162:165], v[212:215], v[76:79]
	v_mfma_f32_16x16x32_bf16 v[72:75], v[170:173], v[212:215], v[72:75]
	v_mfma_f32_16x16x32_bf16 v[60:63], v[162:165], v[220:223], v[60:63]
	v_mfma_f32_16x16x32_bf16 v[56:59], v[170:173], v[220:223], v[56:59]
	v_mfma_f32_16x16x32_bf16 v[44:47], v[162:165], v[228:231], v[44:47]
	v_mfma_f32_16x16x32_bf16 v[40:43], v[170:173], v[228:231], v[40:43]
	v_mfma_f32_16x16x32_bf16 v[92:95], v[166:169], v[208:211], v[92:95]
	v_mfma_f32_16x16x32_bf16 v[88:91], v[174:177], v[208:211], v[88:91]
	v_mfma_f32_16x16x32_bf16 v[76:79], v[166:169], v[216:219], v[76:79]
	v_mfma_f32_16x16x32_bf16 v[72:75], v[174:177], v[216:219], v[72:75]
	v_mfma_f32_16x16x32_bf16 v[60:63], v[166:169], v[224:227], v[60:63]
	v_mfma_f32_16x16x32_bf16 v[56:59], v[174:177], v[224:227], v[56:59]
	v_mfma_f32_16x16x32_bf16 v[44:47], v[166:169], v[232:235], v[44:47]
	v_mfma_f32_16x16x32_bf16 v[40:43], v[174:177], v[232:235], v[40:43]
	s_setprio 0
	s_setprio 1
	v_mfma_f32_16x16x32_bf16 v[84:87], v[178:181], v[204:207], v[84:87]
	v_mfma_f32_16x16x32_bf16 v[80:83], v[196:199], v[204:207], v[80:83]
	v_mfma_f32_16x16x32_bf16 v[68:71], v[178:181], v[212:215], v[68:71]
	v_mfma_f32_16x16x32_bf16 v[64:67], v[196:199], v[212:215], v[64:67]
	v_mfma_f32_16x16x32_bf16 v[52:55], v[178:181], v[220:223], v[52:55]
	v_mfma_f32_16x16x32_bf16 v[48:51], v[196:199], v[220:223], v[48:51]
	v_mfma_f32_16x16x32_bf16 v[32:35], v[178:181], v[228:231], v[32:35]
	v_mfma_f32_16x16x32_bf16 v[36:39], v[196:199], v[228:231], v[36:39]
	v_mfma_f32_16x16x32_bf16 v[84:87], v[182:185], v[208:211], v[84:87]
	v_mfma_f32_16x16x32_bf16 v[80:83], v[200:203], v[208:211], v[80:83]
	v_mfma_f32_16x16x32_bf16 v[68:71], v[182:185], v[216:219], v[68:71]
	v_mfma_f32_16x16x32_bf16 v[64:67], v[200:203], v[216:219], v[64:67]
	v_mfma_f32_16x16x32_bf16 v[52:55], v[182:185], v[224:227], v[52:55]
	v_mfma_f32_16x16x32_bf16 v[48:51], v[200:203], v[224:227], v[48:51]
	v_mfma_f32_16x16x32_bf16 v[32:35], v[182:185], v[232:235], v[32:35]
	v_mfma_f32_16x16x32_bf16 v[36:39], v[200:203], v[232:235], v[36:39]
	s_setprio 0
	s_barrier
	s_add_i32 s14, s14, 2
	s_add_u32 s54, s54, 0x100
	s_addc_u32 s55, s55, 0
	s_add_u32 s7, s7, 0x100
	s_addc_u32 s9, s9, 0
	s_cmp_gt_u32 s14, 29
